# attention loop: K/V LDS-DMA use saddr+32-bit voffset form (SALU base math) instead of per-lane 64-bit VALU address adds
# speedup vs baseline: 1.0055x; 1.0055x over previous
; #define LAS __attribute__((address_space(3)))
; DI int opaque_tid() { int t = threadIdx.x; asm volatile("" : "+v"(t)); return t; }
; #define AT_ISSUE_K(tile, slot) do { const char* g_ = kbu + (size_t)(tile) * (64 * D * 2) + kso; AT_DMA(g_, KRING + (slot) * SLOT + wid * 1024); AT_DMA(g_ + 128, KRING + (slot) * SLOT + 8192 + wid * 1024); } while (0)
; DI void attn_unit(const bf16_t* Q, const bf16_t* Kp, const bf16_t* Vp, bf16_t* O, size_t qrow0, size_t krow0, int ntile, int h, float lam, float lam_init, const float* gsub, LAS unsigned char* lds) {
;     const int tid = opaque_tid(), lane = tid & 63, wid = __builtin_amdgcn_readfirstlane(tid >> 6), r32 = lane & 31, hh = lane >> 5;
;     const int sub = wid & 1, qg = wid >> 1;
;     constexpr int KRING = 0, VRING = 65536, SLOT = 16384;
;     bf16x8 qf[4];
;     { const bf16_t* qp = Q + (qrow0 + 32 * qg + r32) * D + h * 128 + sub * 64 + 8 * hh;
; #pragma unroll
;       for (int d0 = 0; d0 < 4; ++d0) qf[d0] = *(const bf16x8*)(qp + 16 * d0); }
;     f32x16 ot[4];
; #pragma unroll
;     for (int d = 0; d < 4; ++d)
; #pragma unroll
;         for (int i = 0; i < 16; ++i) ot[d][i] = 0.f;
;     float m_run = -1e30f, l_run = 0.f;
;     const char* kbu = (const char*)(Kp + krow0 * D + h * 128); const char* vbu = (const char*)(Vp + krow0 * D + h * 128);
;     unsigned kso, vso0, vso1;
;     { const int kr = 8 * wid + (lane >> 3); const int kc = (lane & 7) ^ ((kr >> 1) & 7); kso = (unsigned)((kr * D + kc * 8) * 2);
;       const int vr0 = 4 * wid + (lane >> 4), vr1 = vr0 + 32; const int vc = (lane & 15) ^ (4 * (vr0 & 3));
;       vso0 = (unsigned)((vr0 * D + vc * 8) * 2); vso1 = (unsigned)((vr1 * D + vc * 8) * 2); }
;     const unsigned ldsb = (unsigned)(unsigned long)lds;
;     ...
;     asm volatile("s_waitcnt lgkmcnt(0)" ::: "memory"); __builtin_amdgcn_s_barrier();
;     AT_ISSUE_K(0, 0); AT_ISSUE_K(1, 1); AT_ISSUE_K(2, 2); AT_ISSUE_K(3, 3); AT_ISSUE_V(0, 0); AT_ISSUE_V(1, 1);
;     { const u32x4 z = {0u, 0u, 0u, 0u}; *(LAS u32x4*)(lds + VRING + 3 * SLOT + tid * 16) = z; *(LAS u32x4*)(lds + VRING + 3 * SLOT + 8192 + tid * 16) = z; }
;     asm volatile("s_waitcnt vmcnt(0) lgkmcnt(0)" ::: "memory"); __builtin_amdgcn_s_barrier(); asm volatile("" ::: "memory");
.LBB0_567:
	s_and_b64 vcc, exec, s[40:41]
	s_cbranch_vccz .LBB0_570
	s_ashr_i32 s54, s56, 8
	s_lshl_b32 s46, s56, 7
	s_mul_i32 s41, s54, 0x1100
	s_and_b32 s46, s46, 0xf80
	s_mul_hi_i32 s40, s54, 0x1100
	s_add_u32 s46, s41, s46
	s_addc_u32 s47, s40, 0
	v_readlane_b32 s40, v253, 57
	v_cmp_lt_u64_e32 vcc, s[46:47], v[238:239]
	v_readlane_b32 s41, v253, 58
	s_and_b64 s[40:41], s[40:41], vcc
	s_and_b64 s[40:41], s[40:41], exec
	v_mov_b32_e32 v1, v206
	s_cselect_b32 s51, s65, s59
	v_readfirstlane_b32 s41, v1
	s_cselect_b32 s50, s64, s58
	s_ashr_i32 s67, s41, 7
	v_and_b32_e32 v6, 31, v1
	s_lshl_b32 s52, s67, 5
	s_ashr_i32 s53, s52, 31
	v_or_b32_e32 v2, s46, v6
	v_mov_b32_e32 v3, s47
	s_ashr_i32 s40, s41, 6
	v_lshl_add_u64 v[34:35], v[2:3], 0, s[52:53]
	s_lshl_b32 s41, s56, 2
	v_lshlrev_b64 v[2:3], 11, v[34:35]
	s_and_b32 s46, s41, 0x380
	s_and_b32 s66, s40, 1
	v_lshl_add_u64 v[2:3], s[50:51], 0, v[2:3]
	s_lshl_b32 s92, s46, 1
	v_bfe_u32 v37, v1, 5, 1
	v_lshl_add_u64 v[2:3], v[2:3], 0, s[92:93]
	s_lshl_b32 s50, s66, 7
	s_mov_b32 s51, s93
	v_lshl_add_u64 v[2:3], v[2:3], 0, s[50:51]
	v_lshlrev_b32_e32 v4, 4, v37
	v_mov_b32_e32 v5, v0
	v_lshl_add_u64 v[2:3], v[2:3], 0, v[4:5]
	flat_load_dwordx4 v[146:149], v[2:3]
	flat_load_dwordx4 v[150:153], v[2:3] offset:32
	flat_load_dwordx4 v[154:157], v[2:3] offset:64
	flat_load_dwordx4 v[158:161], v[2:3] offset:96
	s_mul_hi_i32 s41, s54, 0x880000
	s_mul_i32 s54, s54, 0x880000
	s_add_u32 s47, s60, s54
	s_addc_u32 s50, s61, s41
	s_add_u32 s52, s47, s92
	s_addc_u32 s53, s50, 0
	v_bfe_u32 v2, v1, 3, 3
	s_add_u32 s47, s62, s54
	v_lshl_or_b32 v2, s40, 3, v2
	s_addc_u32 s41, s63, s41
	v_lshrrev_b32_e32 v3, 1, v2
	s_add_u32 s50, s47, s92
	v_xor_b32_e32 v3, v3, v1
	v_bfe_u32 v39, v1, 4, 2
	v_and_b32_e32 v38, 15, v1
	s_addc_u32 s51, s41, 0
	v_lshlrev_b32_e32 v2, 11, v2
	v_lshlrev_b32_e32 v3, 4, v3
	s_movk_i32 s41, 0x70
	v_lshlrev_b32_e32 v4, 6, v39
	v_lshlrev_b32_e32 v5, 4, v38
	v_and_or_b32 v2, v3, s41, v2
	v_lshlrev_b32_e32 v3, 11, v39
	s_lshl_b32 s41, s40, 13
	v_xor_b32_e32 v4, v5, v4
	v_or3_b32 v194, s41, v3, v4
	v_mov_b32_e32 v3, v0
	s_lshl_b32 s68, s40, 10
	s_waitcnt lgkmcnt(0)
	s_barrier
	v_lshl_add_u64 v[198:199], s[52:53], 0, v[2:3]
	v_mov_b32_e32 v252, v2
	s_mov_b64 s[98:99], s[52:53]
	s_add_i32 s41, s68, 0
	s_mov_b32 s47, m0
	s_mov_b32 m0, s41
	s_nop 0
	global_load_lds_dwordx4 v[198:199], off
	s_mov_b32 m0, s47
	s_add_i32 s47, s41, 0x2000
	v_lshl_add_u64 v[2:3], v[198:199], 0, s[90:91]
	s_mov_b32 s52, m0
	s_mov_b32 m0, s47
	s_nop 0
	global_load_lds_dwordx4 v[2:3], off
	s_mov_b32 m0, s52
	s_mov_b64 s[52:53], 0x20000
	v_lshl_add_u64 v[2:3], v[198:199], 0, s[52:53]
	s_add_i32 s47, s41, 0x4000
	s_mov_b32 s52, m0
	s_mov_b32 m0, s47
	s_nop 0
	global_load_lds_dwordx4 v[2:3], off
	s_mov_b32 m0, s52
	s_mov_b64 s[52:53], 0x20080
	s_add_i32 s47, s41, 0x6000
	v_lshl_add_u64 v[2:3], v[198:199], 0, s[52:53]
	s_mov_b32 s52, m0
	s_mov_b32 m0, s47
	s_nop 0
	global_load_lds_dwordx4 v[2:3], off
	s_mov_b32 m0, s52
	s_mov_b64 s[52:53], 0x40000
	v_lshl_add_u64 v[2:3], v[198:199], 0, s[52:53]
	s_add_i32 s47, s41, 0x8000
	s_mov_b32 s52, m0
	s_mov_b32 m0, s47
	s_nop 0
	global_load_lds_dwordx4 v[2:3], off
	s_mov_b32 m0, s52
	s_mov_b64 s[52:53], 0x40080
	s_add_i32 s47, s41, 0xa000
	v_lshl_add_u64 v[2:3], v[198:199], 0, s[52:53]
	s_mov_b32 s52, m0
	s_mov_b32 m0, s47
	s_nop 0
	global_load_lds_dwordx4 v[2:3], off
	s_mov_b32 m0, s52
	s_mov_b64 s[52:53], 0x60000
	v_lshl_add_u64 v[2:3], v[198:199], 0, s[52:53]
	s_add_i32 s47, s41, 0xc000
	s_mov_b32 s52, m0
	s_mov_b32 m0, s47
	s_nop 0
	global_load_lds_dwordx4 v[2:3], off
	s_mov_b32 m0, s52
	s_mov_b64 s[52:53], 0x60080
	s_add_i32 s47, s41, 0xe000
	v_lshl_add_u64 v[2:3], v[198:199], 0, s[52:53]
	s_mov_b32 s52, m0
	s_mov_b32 m0, s47
	s_nop 0
	global_load_lds_dwordx4 v[2:3], off
	s_mov_b32 m0, s52
	v_mov_b32_e32 v195, v0
	v_add_u32_e32 v196, 0x10000, v194
	s_add_i32 s47, s41, 0x10000
	v_lshl_add_u64 v[2:3], s[50:51], 0, v[194:195]
	s_mov_b32 s52, m0
	s_mov_b32 m0, s47
	s_nop 0
	global_load_lds_dwordx4 v[2:3], off
	s_mov_b32 m0, s52
	v_mov_b32_e32 v197, v0
	s_add_i32 s47, s41, 0x12000
	v_lshl_add_u64 v[2:3], s[50:51], 0, v[196:197]
	s_mov_b32 s52, m0
	s_mov_b32 m0, s47
	s_nop 0
	global_load_lds_dwordx4 v[2:3], off
	s_mov_b32 m0, s52
	s_add_u32 s52, s50, 0x20000
	s_addc_u32 s53, s51, 0
	v_lshl_add_u64 v[2:3], s[52:53], 0, v[194:195]
	s_add_i32 s47, s41, 0x14000
	s_mov_b32 s54, m0
	s_mov_b32 m0, s47
	s_nop 0
	global_load_lds_dwordx4 v[2:3], off
	s_mov_b32 m0, s54
	v_lshl_add_u64 v[2:3], s[52:53], 0, v[196:197]
	s_mov_b32 s92, s93
	s_add_i32 s41, s41, 0x16000
	s_mov_b32 s47, m0
	s_mov_b32 m0, s41
	s_nop 0
	global_load_lds_dwordx4 v[2:3], off
	s_mov_b32 m0, s47
	v_lshl_add_u32 v2, v1, 4, 0
	s_mov_b32 s94, s93
	s_mov_b32 s95, s93
	v_mov_b64_e32 v[8:9], s[92:93]
	v_add_u32_e32 v3, 0x1c000, v2
	v_mov_b64_e32 v[10:11], s[94:95]
	v_add_u32_e32 v2, 0x1e000, v2
	ds_write_b128 v2, v[8:11]
	v_lshrrev_b32_e32 v2, 1, v1
	s_lshl_b32 s41, s66, 13
	s_add_i32 s41, s41, 0
	v_bitop3_b32 v2, v37, v2, 7 bitop3:0x78
	ds_write_b128 v3, v[8:11]
	v_lshl_add_u32 v200, v6, 7, s41
	v_lshlrev_b32_e32 v201, 4, v2
	s_waitcnt vmcnt(0) lgkmcnt(0)
	s_barrier
; #define LAS __attribute__((address_space(3)))
; #define MFMA32(a, b, c) __builtin_amdgcn_mfma_f32_32x32x16_bf16((a), (b), (c), 0, 0, 0)
; DI void attn_unit(const bf16_t* Q, const bf16_t* Kp, const bf16_t* Vp, bf16_t* O, size_t qrow0, size_t krow0, int ntile, int h, float lam, float lam_init, const float* gsub, LAS unsigned char* lds) {
;     ...
;     const int q4 = (lane & 15) >> 2, p4 = lane & 3, blk = (lane >> 4) & 1;
;     const int ksw = (r32 >> 1) & 7;
;     const int kro = sub * 8192 + r32 * 128;
;     const int vro = (4 * hh + q4) * 256 + blk * 32 + p4 * 8;
;     f32x16 sc[2], sn[2];
; #pragma unroll
;     for (int kh = 0; kh < 2; ++kh) {
; #pragma unroll
;         for (int i = 0; i < 16; ++i) sc[kh][i] = 0.f;
; #pragma unroll
;         for (int d0 = 0; d0 < 4; ++d0) { const bf16x8 kf = *(const LAS bf16x8*)(lds + KRING + kro + kh * 4096 + (((2 * d0 + hh) ^ ksw) * 16)); sc[kh] = MFMA32(kf, qf[d0], sc[kh]); }
;     }
;     u32x4 pp[4];
; #pragma unroll
;     for (int j = 0; j < 4; ++j) pp[j] = (u32x4){0u, 0u, 0u, 0u};
;     constexpr float AT_TRIG = 16384.f;
;     f32x16 negm;
;     { float mx = fmaxf(fmaxf(sc[0][0], sc[0][1]), sc[0][2]);
; #pragma unroll
;       for (int i = 3; i < 15; i += 2) mx = fmaxf(fmaxf(mx, sc[0][i]), sc[0][i + 1]);
;       mx = fmaxf(mx, sc[0][15]);
; #pragma unroll
;       for (int i = 0; i < 16; i += 2) mx = fmaxf(fmaxf(mx, sc[1][i]), sc[1][i + 1]);
;       mx = fmaxf(mx, __shfl_xor(mx, 32));
; #pragma unroll
;       for (int i = 0; i < 16; ++i) { negm[i] = -mx; sc[0][i] -= mx; sc[1][i] -= mx; } }
;     asm volatile("s_waitcnt lgkmcnt(0)" ::: "memory"); __builtin_amdgcn_s_barrier(); asm volatile("" ::: "memory");
;     const bool shifted = wid >= 4;
;     float ps = 0.f;
;     if (shifted) {
; #pragma unroll
;         for (int kh = 0; kh < 2; ++kh)
; #pragma unroll
;             for (int i = 0; i < 16; ++i) { sc[kh][i] = __builtin_amdgcn_exp2f(sc[kh][i]); ps += sc[kh][i]; }
;         l_run += ps;
;     }
	v_add_u32_e32 v23, v200, v201
	ds_read_b128 v[2:5], v23
	v_bfe_u32 v22, v1, 1, 3
	v_bitop3_b32 v18, v37, v22, 2 bitop3:0x36
	v_lshlrev_b32_e32 v202, 4, v18
	v_add_u32_e32 v36, v200, v202
	ds_read_b128 v[18:21], v36
	s_waitcnt vmcnt(0) lgkmcnt(0)
	v_mfma_f32_32x32x16_bf16 v[2:17], v[2:5], v[146:149], 0
	ds_read_b128 v[40:43], v36 offset:4096
	s_cmp_gt_i32 s40, 3
	s_cselect_b64 s[52:53], -1, 0
	s_cmp_lt_i32 s40, 4
	s_cselect_b64 s[54:55], -1, 0
	s_mov_b32 s77, 0
	v_mfma_f32_32x32x16_bf16 v[2:17], v[18:21], v[150:153], v[2:17]
	v_bitop3_b32 v18, v37, v22, 4 bitop3:0x36
	v_lshlrev_b32_e32 v203, 4, v18
	v_add_u32_e32 v44, v200, v203
	ds_read_b128 v[18:21], v44
	s_waitcnt lgkmcnt(0)
	v_mfma_f32_32x32x16_bf16 v[2:17], v[18:21], v[154:157], v[2:17]
	v_bitop3_b32 v18, v37, v22, 6 bitop3:0x36
	v_lshlrev_b32_e32 v204, 4, v18
	v_add_u32_e32 v45, v200, v204
	ds_read_b128 v[18:21], v45
	s_waitcnt lgkmcnt(0)
	v_mfma_f32_32x32x16_bf16 v[2:17], v[18:21], v[158:161], v[2:17]
	ds_read_b128 v[18:21], v23 offset:4096
	s_nop 10
	v_max_f32_e32 v36, v3, v3
	s_waitcnt lgkmcnt(0)
	v_mfma_f32_32x32x16_bf16 v[18:33], v[18:21], v[146:149], 0
	v_mfma_f32_32x32x16_bf16 v[18:33], v[40:43], v[150:153], v[18:33]
	ds_read_b128 v[40:43], v44 offset:4096
	s_waitcnt lgkmcnt(0)
	v_mfma_f32_32x32x16_bf16 v[18:33], v[40:43], v[154:157], v[18:33]
	ds_read_b128 v[40:43], v45 offset:4096
	s_waitcnt lgkmcnt(0)
	s_barrier
	s_waitcnt lgkmcnt(0)
	v_mfma_f32_32x32x16_bf16 v[18:33], v[40:43], v[158:161], v[18:33]
	v_max_f32_e32 v40, v2, v2
	v_max_f32_e32 v36, v40, v36
	v_max3_f32 v36, v36, v4, v5
	v_max3_f32 v36, v36, v6, v7
	v_max3_f32 v36, v36, v8, v9
	v_max3_f32 v36, v36, v10, v11
	v_max3_f32 v36, v36, v12, v13
	v_max3_f32 v36, v36, v14, v15
	v_max3_f32 v36, v36, v16, v17
	s_nop 2
	v_max3_f32 v36, v36, v18, v19
	v_max3_f32 v36, v36, v20, v21
	v_max3_f32 v36, v36, v22, v23
	v_max3_f32 v36, v36, v24, v25
	v_and_b32_e32 v41, 64, v209
	v_max3_f32 v36, v36, v26, v27
	v_xor_b32_e32 v40, 32, v209
	v_add_u32_e32 v41, 64, v41
	v_max3_f32 v36, v36, v28, v29
	v_cmp_lt_i32_e32 vcc, v40, v41
	v_max3_f32 v36, v36, v30, v31
	v_max3_f32 v36, v36, v32, v33
	v_cndmask_b32_e32 v40, v209, v40, vcc
	v_lshlrev_b32_e32 v191, 2, v40
	ds_bpermute_b32 v40, v191, v36
	s_and_b64 vcc, exec, s[54:55]
	s_waitcnt lgkmcnt(0)
	v_max_f32_e32 v40, v40, v40
	v_max_f32_e32 v36, v36, v40
	v_pk_add_f32 v[66:67], v[2:3], v[36:37] op_sel_hi:[1,0] neg_lo:[0,1] neg_hi:[0,1]
	v_pk_add_f32 v[82:83], v[18:19], v[36:37] op_sel_hi:[1,0] neg_lo:[0,1] neg_hi:[0,1]
	v_pk_add_f32 v[68:69], v[4:5], v[36:37] op_sel_hi:[1,0] neg_lo:[0,1] neg_hi:[0,1]
	v_pk_add_f32 v[84:85], v[20:21], v[36:37] op_sel_hi:[1,0] neg_lo:[0,1] neg_hi:[0,1]
	v_pk_add_f32 v[70:71], v[6:7], v[36:37] op_sel_hi:[1,0] neg_lo:[0,1] neg_hi:[0,1]
	v_pk_add_f32 v[86:87], v[22:23], v[36:37] op_sel_hi:[1,0] neg_lo:[0,1] neg_hi:[0,1]
	v_pk_add_f32 v[72:73], v[8:9], v[36:37] op_sel_hi:[1,0] neg_lo:[0,1] neg_hi:[0,1]
	v_pk_add_f32 v[88:89], v[24:25], v[36:37] op_sel_hi:[1,0] neg_lo:[0,1] neg_hi:[0,1]
	v_pk_add_f32 v[74:75], v[10:11], v[36:37] op_sel_hi:[1,0] neg_lo:[0,1] neg_hi:[0,1]
	v_pk_add_f32 v[90:91], v[26:27], v[36:37] op_sel_hi:[1,0] neg_lo:[0,1] neg_hi:[0,1]
	v_pk_add_f32 v[76:77], v[12:13], v[36:37] op_sel_hi:[1,0] neg_lo:[0,1] neg_hi:[0,1]
	v_pk_add_f32 v[92:93], v[28:29], v[36:37] op_sel_hi:[1,0] neg_lo:[0,1] neg_hi:[0,1]
	v_pk_add_f32 v[78:79], v[14:15], v[36:37] op_sel_hi:[1,0] neg_lo:[0,1] neg_hi:[0,1]
	v_pk_add_f32 v[94:95], v[30:31], v[36:37] op_sel_hi:[1,0] neg_lo:[0,1] neg_hi:[0,1]
	v_pk_add_f32 v[80:81], v[16:17], v[36:37] op_sel_hi:[1,0] neg_lo:[0,1] neg_hi:[0,1]
	v_pk_add_f32 v[96:97], v[32:33], v[36:37] op_sel_hi:[1,0] neg_lo:[0,1] neg_hi:[0,1]
	s_cbranch_vccnz .LBB0_571
	v_exp_f32_e32 v66, v66
	v_exp_f32_e32 v67, v67
	v_exp_f32_e32 v68, v68
	v_exp_f32_e32 v69, v69
	v_add_f32_e32 v2, 0, v66
	v_exp_f32_e32 v70, v70
	v_add_f32_e32 v2, v67, v2
	v_exp_f32_e32 v71, v71
	v_add_f32_e32 v2, v68, v2
	v_exp_f32_e32 v72, v72
	v_add_f32_e32 v2, v69, v2
	v_exp_f32_e32 v73, v73
	v_add_f32_e32 v2, v70, v2
	v_exp_f32_e32 v74, v74
	v_add_f32_e32 v2, v71, v2
	v_exp_f32_e32 v75, v75
	v_add_f32_e32 v2, v72, v2
	v_exp_f32_e32 v76, v76
	v_add_f32_e32 v2, v73, v2
	v_exp_f32_e32 v77, v77
	v_add_f32_e32 v2, v74, v2
	v_exp_f32_e32 v78, v78
	v_add_f32_e32 v2, v75, v2
	v_exp_f32_e32 v79, v79
	v_add_f32_e32 v2, v76, v2
	v_exp_f32_e32 v80, v80
	v_add_f32_e32 v2, v77, v2
	v_exp_f32_e32 v81, v81
	v_add_f32_e32 v2, v78, v2
	v_exp_f32_e32 v82, v82
	v_add_f32_e32 v2, v79, v2
	v_exp_f32_e32 v83, v83
	v_add_f32_e32 v2, v80, v2
	v_exp_f32_e32 v84, v84
	v_add_f32_e32 v2, v81, v2
	v_exp_f32_e32 v85, v85
	v_add_f32_e32 v2, v82, v2
	v_exp_f32_e32 v86, v86
	v_add_f32_e32 v2, v83, v2
	v_exp_f32_e32 v87, v87
	v_add_f32_e32 v2, v84, v2
	v_exp_f32_e32 v88, v88
	v_add_f32_e32 v2, v85, v2
	v_exp_f32_e32 v89, v89
	v_add_f32_e32 v2, v86, v2
	v_exp_f32_e32 v90, v90
	v_add_f32_e32 v2, v87, v2
	v_exp_f32_e32 v91, v91
	v_add_f32_e32 v2, v88, v2
	v_exp_f32_e32 v92, v92
	v_add_f32_e32 v2, v89, v2
	v_exp_f32_e32 v93, v93
	v_add_f32_e32 v2, v90, v2
	v_exp_f32_e32 v94, v94
	v_add_f32_e32 v2, v91, v2
	v_exp_f32_e32 v95, v95
	v_add_f32_e32 v2, v92, v2
	v_exp_f32_e32 v96, v96
	v_add_f32_e32 v2, v93, v2
	v_exp_f32_e32 v97, v97
	v_add_f32_e32 v2, v94, v2
	v_add_f32_e32 v2, v95, v2
	v_add_f32_e32 v2, v96, v2
	v_add_f32_e32 v220, v97, v2
	v_add_f32_e32 v213, 0, v220
	s_branch .LBB0_572

; #define LAS __attribute__((address_space(3)))
; #define MFMA32(a, b, c) __builtin_amdgcn_mfma_f32_32x32x16_bf16((a), (b), (c), 0, 0, 0)
; #define AT_ISSUE_K(tile, slot) do { const char* g_ = kbu + (size_t)(tile) * (64 * D * 2) + kso; AT_DMA(g_, KRING + (slot) * SLOT + wid * 1024); AT_DMA(g_ + 128, KRING + (slot) * SLOT + 8192 + wid * 1024); } while (0)
; #define AT_ISSUE_V(tile, slot) do { const char* g_ = vbu + (size_t)(tile) * (64 * D * 2); AT_DMA(g_ + vso0, VRING + (slot) * SLOT + wid * 1024); AT_DMA(g_ + vso1, VRING + (slot) * SLOT + 8192 + wid * 1024); } while (0)
; DI void attn_unit(const bf16_t* Q, const bf16_t* Kp, const bf16_t* Vp, bf16_t* O, size_t qrow0, size_t krow0, int ntile, int h, float lam, float lam_init, const float* gsub, LAS unsigned char* lds) {
;     ...
;       {
;         { const int tk = (t + 4 < ntile) ? t + 4 : ntile - 1; AT_ISSUE_K(tk, ks0); const int tv = (t + 2 < ntile) ? t + 2 : ntile - 1; AT_ISSUE_V(tv, vs1); }
;         LAS unsigned char* kb = lds + KRING + ks1 * SLOT + kro;
;         LAS unsigned char* vb = lds + VRING + vsm1 * SLOT + vro;
;         __builtin_amdgcn_s_setprio(1);
;         { bf16x8 ql[4];
; #pragma unroll
;           for (int d0 = 0; d0 < 4; ++d0) ql[d0] = qf[d0];
; #pragma unroll
;           for (int kh = 0; kh < 2; ++kh) {
;             bf16x8 kf[4];
; #pragma unroll
;             for (int e = 0; e < 4; ++e) kf[e] = *(const LAS bf16x8*)(kb + kh * 4096 + (((2 * e + hh) ^ ksw) * 16));
;             sn[kh] = MFMA32(kf[0], ql[0], negm);
; #pragma unroll
;             for (int d0 = 1; d0 < 4; ++d0) sn[kh] = MFMA32(kf[d0], ql[d0], sn[kh]);
;             __builtin_amdgcn_sched_barrier(0);
;           } }
; #pragma unroll
;         for (int j = 0; j < 4; ++j) {
;             s16x4 lo[4], hi[4];
; #pragma unroll
;             for (int e = 0; e < 4; ++e) { LAS unsigned char* vp = vb + j * 4096 + ((e ^ q4) * 64);
;                 lo[e] = __builtin_bit_cast(s16x4, __builtin_amdgcn_ds_read_tr16_b64_v4i16((LAS s16x4*)vp));
;                 hi[e] = __builtin_bit_cast(s16x4, __builtin_amdgcn_ds_read_tr16_b64_v4i16((LAS s16x4*)(vp + 2048))); }
; #pragma unroll
;             for (int e = 0; e < 4; ++e) ot[e] = MFMA32(__builtin_shufflevector(lo[e], hi[e], 0, 1, 2, 3, 4, 5, 6, 7), __builtin_bit_cast(bf16x8, pp[j]), ot[e]);
;             __builtin_amdgcn_sched_barrier(0);
;         }
;         __builtin_amdgcn_s_setprio(0);
.LBB0_573:
	s_lshl_b32 s80, s74, 14
	s_lshl_b32 s78, s70, 14
	s_setprio 1
	v_add_u32_e32 v1, s80, v200
	v_add_u32_e32 v226, v1, v201
	v_add_u32_e32 v207, v1, v202
	v_add_u32_e32 v221, v1, v203
	v_add_u32_e32 v1, v1, v204
	ds_read_b128 v[182:185], v226
	ds_read_b128 v[222:225], v207
	ds_read_b128 v[228:231], v221
	ds_read_b128 v[240:243], v1
	ds_read_b128 v[244:247], v226 offset:4096
	ds_read_b128 v[248:251], v207 offset:4096
	v_add_u32_e32 v227, s78, v219
	v_add_u32_e32 v226, v227, v218
	v_add_u32_e32 v207, v227, v217
	v_add_u32_e32 v235, v227, v216
	v_add_u32_e32 v227, v227, v214
	s_min_u32 s40, s76, 63
	s_add_i32 s40, s40, 4
	s_lshl_b32 s40, s40, 17
	s_add_u32 s40, s98, s40
	s_addc_u32 s41, s99, 0
	s_lshl_b32 s75, s77, 14
	s_add_i32 s92, s75, s68
	s_mov_b32 vcc_lo, m0
	s_mov_b32 m0, s92
	s_nop 0
	global_load_lds_dwordx4 v252, s[40:41]
	s_mov_b32 m0, vcc_lo
	s_add_u32 s40, s40, 0x80
	s_addc_u32 s41, s41, 0
	s_add_i32 s92, s75, s71
	s_mov_b32 vcc_lo, m0
	s_mov_b32 m0, s92
	s_nop 0
	global_load_lds_dwordx4 v252, s[40:41]
	s_mov_b32 m0, vcc_lo
	s_waitcnt lgkmcnt(5)
	v_mfma_f32_32x32x16_bf16 v[114:129], v[182:185], v[146:149], v[98:113]
	ds_read_b128 v[182:185], v221 offset:4096
	s_waitcnt lgkmcnt(5)
	v_mfma_f32_32x32x16_bf16 v[114:129], v[222:225], v[150:153], v[114:129]
	ds_read_b128 v[222:225], v1 offset:4096
	s_add_i32 s75, s76, 2
	s_min_u32 s40, s75, 0x43
	s_lshl_b32 s40, s40, 17
	s_add_u32 s40, s50, s40
	s_addc_u32 s41, s51, 0
	s_lshl_b32 s79, s69, 14
	s_add_i32 s77, s72, s79
	s_mov_b32 vcc_lo, m0
	s_mov_b32 m0, s77
	s_nop 0
	global_load_lds_dwordx4 v194, s[40:41]
	s_mov_b32 m0, vcc_lo
	s_waitcnt lgkmcnt(5)
	v_mfma_f32_32x32x16_bf16 v[114:129], v[228:231], v[154:157], v[114:129]
	ds_read_b64_tr_b16 v[228:229], v226
	ds_read_b64_tr_b16 v[230:231], v226 offset:2048
	s_waitcnt lgkmcnt(6)
	v_mfma_f32_32x32x16_bf16 v[114:129], v[240:243], v[158:161], v[114:129]
	ds_read_b64_tr_b16 v[240:241], v207
	ds_read_b64_tr_b16 v[242:243], v207 offset:2048
	s_add_i32 s77, s73, s79
	s_mov_b32 vcc_lo, m0
	s_mov_b32 m0, s77
	s_nop 0
	global_load_lds_dwordx4 v196, s[40:41]
	s_mov_b32 m0, vcc_lo
	s_waitcnt lgkmcnt(7)
	v_mfma_f32_32x32x16_bf16 v[130:145], v[244:247], v[146:149], v[98:113]
	ds_read_b64_tr_b16 v[244:245], v235
	ds_read_b64_tr_b16 v[246:247], v235 offset:2048
	s_waitcnt lgkmcnt(8)
	v_mfma_f32_32x32x16_bf16 v[130:145], v[248:251], v[150:153], v[130:145]
	ds_read_b64_tr_b16 v[248:249], v227
	ds_read_b64_tr_b16 v[250:251], v227 offset:2048
	s_waitcnt lgkmcnt(9)
	v_mfma_f32_32x32x16_bf16 v[130:145], v[182:185], v[154:157], v[130:145]
	ds_read_b64_tr_b16 v[182:183], v226 offset:4096
	ds_read_b64_tr_b16 v[184:185], v226 offset:6144
	s_waitcnt lgkmcnt(10)
	v_mfma_f32_32x32x16_bf16 v[130:145], v[222:225], v[158:161], v[130:145]
	ds_read_b64_tr_b16 v[222:223], v207 offset:4096
	ds_read_b64_tr_b16 v[224:225], v207 offset:6144
	s_waitcnt lgkmcnt(10)
	v_mfma_f32_32x32x16_bf16 v[50:65], v[228:231], v[174:177], v[50:65]
	ds_read_b64_tr_b16 v[228:229], v235 offset:4096
	ds_read_b64_tr_b16 v[230:231], v235 offset:6144
	s_waitcnt lgkmcnt(10)
	v_mfma_f32_32x32x16_bf16 v[34:49], v[240:243], v[174:177], v[34:49]
	ds_read_b64_tr_b16 v[240:241], v227 offset:4096
	ds_read_b64_tr_b16 v[242:243], v227 offset:6144
	s_waitcnt lgkmcnt(10)
	v_mfma_f32_32x32x16_bf16 v[18:33], v[244:247], v[174:177], v[18:33]
	ds_read_b64_tr_b16 v[244:245], v226 offset:8192
	ds_read_b64_tr_b16 v[246:247], v226 offset:10240
	s_waitcnt lgkmcnt(10)
	v_mfma_f32_32x32x16_bf16 v[2:17], v[248:251], v[174:177], v[2:17]
	ds_read_b64_tr_b16 v[248:249], v207 offset:8192
	ds_read_b64_tr_b16 v[250:251], v207 offset:10240
	s_waitcnt lgkmcnt(10)
	v_mfma_f32_32x32x16_bf16 v[50:65], v[182:185], v[170:173], v[50:65]
	ds_read_b64_tr_b16 v[182:183], v235 offset:8192
	ds_read_b64_tr_b16 v[184:185], v235 offset:10240
	s_waitcnt lgkmcnt(10)
	v_mfma_f32_32x32x16_bf16 v[34:49], v[222:225], v[170:173], v[34:49]
	ds_read_b64_tr_b16 v[222:223], v227 offset:8192
	ds_read_b64_tr_b16 v[224:225], v227 offset:10240
	s_waitcnt lgkmcnt(10)
	v_mfma_f32_32x32x16_bf16 v[18:33], v[228:231], v[170:173], v[18:33]
	ds_read_b64_tr_b16 v[228:229], v226 offset:12288
	ds_read_b64_tr_b16 v[230:231], v226 offset:14336
	s_waitcnt lgkmcnt(10)
	v_mfma_f32_32x32x16_bf16 v[2:17], v[240:243], v[170:173], v[2:17]
	ds_read_b64_tr_b16 v[240:241], v207 offset:12288
	ds_read_b64_tr_b16 v[242:243], v207 offset:14336
	s_waitcnt lgkmcnt(10)
	v_mfma_f32_32x32x16_bf16 v[50:65], v[244:247], v[166:169], v[50:65]
	ds_read_b64_tr_b16 v[244:245], v235 offset:12288
	ds_read_b64_tr_b16 v[246:247], v235 offset:14336
	s_waitcnt lgkmcnt(10)
	v_mfma_f32_32x32x16_bf16 v[34:49], v[248:251], v[166:169], v[34:49]
	ds_read_b64_tr_b16 v[248:249], v227 offset:12288
	ds_read_b64_tr_b16 v[250:251], v227 offset:14336
	s_waitcnt lgkmcnt(10)
	v_mfma_f32_32x32x16_bf16 v[18:33], v[182:185], v[166:169], v[18:33]
	s_waitcnt lgkmcnt(8)
	v_mfma_f32_32x32x16_bf16 v[2:17], v[222:225], v[166:169], v[2:17]
	s_waitcnt lgkmcnt(6)
	v_mfma_f32_32x32x16_bf16 v[50:65], v[228:231], v[162:165], v[50:65]
	s_waitcnt lgkmcnt(4)
	v_mfma_f32_32x32x16_bf16 v[34:49], v[240:243], v[162:165], v[34:49]
	s_waitcnt lgkmcnt(2)
	v_mfma_f32_32x32x16_bf16 v[18:33], v[244:247], v[162:165], v[18:33]
	s_waitcnt lgkmcnt(0)
	v_mfma_f32_32x32x16_bf16 v[2:17], v[248:251], v[162:165], v[2:17]
	s_setprio 0
	v_cndmask_b32_e64 v1, 0, 1, s[54:55]
	v_cmp_ne_u32_e64 s[40:41], 1, v1
	s_andn2_b64 vcc, exec, s[54:55]
	s_cbranch_vccnz .LBB0_575
; DI void attn_unit(const bf16_t* Q, const bf16_t* Kp, const bf16_t* Vp, bf16_t* O, size_t qrow0, size_t krow0, int ntile, int h, float lam, float lam_init, const float* gsub, LAS unsigned char* lds) {
;     ...
;         if (!shifted) {
;             ps = 0.f;
; #pragma unroll
;             for (int kh = 0; kh < 2; ++kh)
; #pragma unroll
;                 for (int i = 0; i < 16; ++i) { sc[kh][i] = __builtin_amdgcn_exp2f(sc[kh][i]); ps += sc[kh][i]; }
;             l_run += ps;
;         }
	v_exp_f32_e32 v66, v66
	v_exp_f32_e32 v67, v67
	v_exp_f32_e32 v68, v68
	v_exp_f32_e32 v69, v69
	v_add_f32_e32 v1, 0, v66
	v_exp_f32_e32 v70, v70
	v_add_f32_e32 v1, v67, v1
	v_exp_f32_e32 v71, v71
	v_add_f32_e32 v1, v68, v1
	v_exp_f32_e32 v72, v72
	v_add_f32_e32 v1, v69, v1
	v_exp_f32_e32 v73, v73
	v_add_f32_e32 v1, v70, v1
	v_exp_f32_e32 v74, v74
	v_add_f32_e32 v1, v71, v1
	v_exp_f32_e32 v75, v75
	v_add_f32_e32 v1, v72, v1
	v_exp_f32_e32 v76, v76
	v_add_f32_e32 v1, v73, v1
	v_exp_f32_e32 v77, v77
	v_add_f32_e32 v1, v74, v1
	v_exp_f32_e32 v78, v78
	v_add_f32_e32 v1, v75, v1
	v_exp_f32_e32 v79, v79
	v_add_f32_e32 v1, v76, v1
	v_exp_f32_e32 v80, v80
	v_add_f32_e32 v1, v77, v1
	v_exp_f32_e32 v81, v81
	v_add_f32_e32 v1, v78, v1
	v_exp_f32_e32 v82, v82
	v_add_f32_e32 v1, v79, v1
	v_exp_f32_e32 v83, v83
	v_add_f32_e32 v1, v80, v1
	v_exp_f32_e32 v84, v84
	v_add_f32_e32 v1, v81, v1
	v_exp_f32_e32 v85, v85
	v_add_f32_e32 v1, v82, v1
	v_exp_f32_e32 v86, v86
	v_add_f32_e32 v1, v83, v1
	v_exp_f32_e32 v87, v87
	v_add_f32_e32 v1, v84, v1
	v_exp_f32_e32 v88, v88
	v_add_f32_e32 v1, v85, v1
	v_exp_f32_e32 v89, v89
	v_add_f32_e32 v1, v86, v1
	v_exp_f32_e32 v90, v90
	v_add_f32_e32 v1, v87, v1
	v_exp_f32_e32 v91, v91
	v_add_f32_e32 v1, v88, v1
	v_exp_f32_e32 v92, v92
	v_add_f32_e32 v1, v89, v1
	v_exp_f32_e32 v93, v93
	v_add_f32_e32 v1, v90, v1
	v_exp_f32_e32 v94, v94
	v_add_f32_e32 v1, v91, v1
	v_exp_f32_e32 v95, v95
	v_add_f32_e32 v1, v92, v1
	v_exp_f32_e32 v96, v96
	v_add_f32_e32 v1, v93, v1
	v_exp_f32_e32 v97, v97
	v_add_f32_e32 v1, v94, v1
	v_add_f32_e32 v1, v95, v1
	v_add_f32_e32 v1, v96, v1
	v_add_f32_e32 v220, v97, v1
	v_add_f32_e32 v213, v213, v220

; #define LAS __attribute__((address_space(3)))
; DI unsigned cvtpk(float lo, float hi) { f32x2_t v = {lo, hi}; bf16x2_t b = __builtin_convertvector(v, bf16x2_t); return __builtin_bit_cast(unsigned, b); }
; DI void attn_unit(const bf16_t* Q, const bf16_t* Kp, const bf16_t* Vp, bf16_t* O, size_t qrow0, size_t krow0, int ntile, int h, float lam, float lam_init, const float* gsub, LAS unsigned char* lds) {
;     ...
;         for (int kh = 0; kh < 2; ++kh)
; #pragma unroll
;             for (int s2 = 0; s2 < 2; ++s2) { u32x4 pa; pa.x = cvtpk(sc[kh][8 * s2], sc[kh][8 * s2 + 1]); pa.y = cvtpk(sc[kh][8 * s2 + 2], sc[kh][8 * s2 + 3]); pa.z = cvtpk(sc[kh][8 * s2 + 4], sc[kh][8 * s2 + 5]); pa.w = cvtpk(sc[kh][8 * s2 + 6], sc[kh][8 * s2 + 7]);
;                 pp[2 * kh + s2] = pa; }
;     ...
;         const int t1 = t + 1;
;         { const int tk = (t1 + 4 < ntile) ? t1 + 4 : ntile - 1; AT_ISSUE_K(tk, ks0); const int tv = (t1 + 2 < ntile) ? t1 + 2 : ntile - 1; AT_ISSUE_V(tv, vs1); }
;         LAS unsigned char* kb = lds + KRING + ks1 * SLOT + kro;
;         LAS unsigned char* vb = lds + VRING + vsm1 * SLOT + vro;
;         __builtin_amdgcn_s_setprio(1);
;         { bf16x8 ql[4];
; #pragma unroll
;           for (int d0 = 0; d0 < 4; ++d0) ql[d0] = qf[d0];
; #pragma unroll
;           for (int kh = 0; kh < 2; ++kh) {
;             bf16x8 kf[4];
; #pragma unroll
;             for (int e = 0; e < 4; ++e) kf[e] = *(const LAS bf16x8*)(kb + kh * 4096 + (((2 * e + hh) ^ ksw) * 16));
;             sc[kh] = MFMA32(kf[0], ql[0], negm);
; #pragma unroll
;             for (int d0 = 1; d0 < 4; ++d0) sc[kh] = MFMA32(kf[d0], ql[d0], sc[kh]);
;             __builtin_amdgcn_sched_barrier(0);
;           } }
; #pragma unroll
;         for (int j = 0; j < 4; ++j) {
;             s16x4 lo[4], hi[4];
; #pragma unroll
;             for (int e = 0; e < 4; ++e) { LAS unsigned char* vp = vb + j * 4096 + ((e ^ q4) * 64);
;                 lo[e] = __builtin_bit_cast(s16x4, __builtin_amdgcn_ds_read_tr16_b64_v4i16((LAS s16x4*)vp));
;                 hi[e] = __builtin_bit_cast(s16x4, __builtin_amdgcn_ds_read_tr16_b64_v4i16((LAS s16x4*)(vp + 2048))); }
; #pragma unroll
;             for (int e = 0; e < 4; ++e) ot[e] = MFMA32(__builtin_shufflevector(lo[e], hi[e], 0, 1, 2, 3, 4, 5, 6, 7), __builtin_bit_cast(bf16x8, pp[j]), ot[e]);
;             __builtin_amdgcn_sched_barrier(0);
;         }
.LBB0_579:
	s_add_i32 s77, s74, 1
	s_and_b32 s77, s77, 3
	s_addk_i32 s78, 0x4000
	s_and_b32 s78, s78, 0xc000
	s_setprio 1
	v_lshl_add_u32 v1, s77, 14, v200
	v_add_u32_e32 v226, v1, v201
	v_add_u32_e32 v207, v1, v202
	v_add_u32_e32 v221, v1, v203
	v_add_u32_e32 v1, v1, v204
	ds_read_b128 v[182:185], v226
	ds_read_b128 v[222:225], v207
	ds_read_b128 v[228:231], v221
	ds_read_b128 v[240:243], v1
	ds_read_b128 v[244:247], v226 offset:4096
	ds_read_b128 v[248:251], v207 offset:4096
	v_add_u32_e32 v227, s78, v219
	v_add_u32_e32 v226, v227, v218
	v_add_u32_e32 v207, v227, v217
	v_add_u32_e32 v235, v227, v216
	v_add_u32_e32 v227, v227, v214
	v_cvt_pk_bf16_f32 v170, v66, v67
	v_cvt_pk_bf16_f32 v171, v68, v69
	v_cvt_pk_bf16_f32 v172, v70, v71
	v_cvt_pk_bf16_f32 v173, v72, v73
	v_cvt_pk_bf16_f32 v174, v74, v75
	v_cvt_pk_bf16_f32 v175, v76, v77
	v_cvt_pk_bf16_f32 v176, v78, v79
	v_cvt_pk_bf16_f32 v177, v80, v81
	v_cvt_pk_bf16_f32 v166, v82, v83
	v_cvt_pk_bf16_f32 v167, v84, v85
	v_cvt_pk_bf16_f32 v168, v86, v87
	v_cvt_pk_bf16_f32 v169, v88, v89
	v_cvt_pk_bf16_f32 v162, v90, v91
	v_cvt_pk_bf16_f32 v163, v92, v93
	v_cvt_pk_bf16_f32 v164, v94, v95
	v_cvt_pk_bf16_f32 v165, v96, v97
	s_min_u32 s81, s76, 62
	s_add_i32 s81, s81, 5
	s_lshl_b32 s81, s81, 17
	s_add_u32 s82, s98, s81
	s_addc_u32 s83, s99, 0
	s_add_i32 s81, s80, s68
	s_mov_b32 vcc_lo, m0
	s_mov_b32 m0, s81
	s_nop 0
	global_load_lds_dwordx4 v252, s[82:83]
	s_mov_b32 m0, vcc_lo
	s_waitcnt lgkmcnt(5)
	v_mfma_f32_32x32x16_bf16 v[66:81], v[182:185], v[146:149], v[98:113]
	ds_read_b128 v[182:185], v221 offset:4096
	s_waitcnt lgkmcnt(5)
	v_mfma_f32_32x32x16_bf16 v[66:81], v[222:225], v[150:153], v[66:81]
	ds_read_b128 v[222:225], v1 offset:4096
	s_add_u32 s82, s82, 0x80
	s_addc_u32 s83, s83, 0
	s_add_i32 s81, s80, s71
	s_mov_b32 vcc_lo, m0
	s_mov_b32 m0, s81
	s_nop 0
	global_load_lds_dwordx4 v252, s[82:83]
	s_mov_b32 m0, vcc_lo
	s_waitcnt lgkmcnt(5)
	v_mfma_f32_32x32x16_bf16 v[66:81], v[228:231], v[154:157], v[66:81]
	ds_read_b64_tr_b16 v[228:229], v226
	ds_read_b64_tr_b16 v[230:231], v226 offset:2048
	s_waitcnt lgkmcnt(6)
	v_mfma_f32_32x32x16_bf16 v[66:81], v[240:243], v[158:161], v[66:81]
	ds_read_b64_tr_b16 v[240:241], v207
	ds_read_b64_tr_b16 v[242:243], v207 offset:2048
	s_min_u32 s80, s76, 64
	s_lshl_b32 s80, s80, 17
	s_add_u32 s80, s50, s80
	s_addc_u32 s81, s51, 0
	s_add_u32 s80, s80, 0x60000
	s_addc_u32 s81, s81, 0
	s_addk_i32 s79, 0x4000
	s_or_b32 s82, s79, 0x10000
	s_add_i32 s82, s82, s68
	s_or_b32 s79, s79, 0x12000
	s_mov_b32 vcc_lo, m0
	s_mov_b32 m0, s82
	s_nop 0
	global_load_lds_dwordx4 v194, s[80:81]
	s_mov_b32 m0, vcc_lo
	s_waitcnt lgkmcnt(7)
	v_mfma_f32_32x32x16_bf16 v[82:97], v[244:247], v[146:149], v[98:113]
	ds_read_b64_tr_b16 v[244:245], v235
	ds_read_b64_tr_b16 v[246:247], v235 offset:2048
	s_waitcnt lgkmcnt(8)
	v_mfma_f32_32x32x16_bf16 v[82:97], v[248:251], v[150:153], v[82:97]
	ds_read_b64_tr_b16 v[248:249], v227
	ds_read_b64_tr_b16 v[250:251], v227 offset:2048
	s_add_i32 s79, s79, s68
	s_mov_b32 vcc_lo, m0
	s_mov_b32 m0, s79
	s_nop 0
	global_load_lds_dwordx4 v196, s[80:81]
	s_mov_b32 m0, vcc_lo
	s_waitcnt lgkmcnt(9)
	v_mfma_f32_32x32x16_bf16 v[82:97], v[182:185], v[154:157], v[82:97]
	ds_read_b64_tr_b16 v[182:183], v226 offset:4096
	ds_read_b64_tr_b16 v[184:185], v226 offset:6144
	s_waitcnt lgkmcnt(10)
	v_mfma_f32_32x32x16_bf16 v[82:97], v[222:225], v[158:161], v[82:97]
	ds_read_b64_tr_b16 v[222:223], v207 offset:4096
	ds_read_b64_tr_b16 v[224:225], v207 offset:6144
	s_waitcnt lgkmcnt(10)
	v_mfma_f32_32x32x16_bf16 v[50:65], v[228:231], v[170:173], v[50:65]
	ds_read_b64_tr_b16 v[228:229], v235 offset:4096
	ds_read_b64_tr_b16 v[230:231], v235 offset:6144
	s_waitcnt lgkmcnt(10)
	v_mfma_f32_32x32x16_bf16 v[34:49], v[240:243], v[170:173], v[34:49]
	ds_read_b64_tr_b16 v[240:241], v227 offset:4096
	ds_read_b64_tr_b16 v[242:243], v227 offset:6144
	s_waitcnt lgkmcnt(10)
	v_mfma_f32_32x32x16_bf16 v[18:33], v[244:247], v[170:173], v[18:33]
	ds_read_b64_tr_b16 v[244:245], v226 offset:8192
	ds_read_b64_tr_b16 v[246:247], v226 offset:10240
	s_waitcnt lgkmcnt(10)
	v_mfma_f32_32x32x16_bf16 v[2:17], v[248:251], v[170:173], v[2:17]
	ds_read_b64_tr_b16 v[248:249], v207 offset:8192
	ds_read_b64_tr_b16 v[250:251], v207 offset:10240
	s_waitcnt lgkmcnt(10)
	v_mfma_f32_32x32x16_bf16 v[50:65], v[182:185], v[174:177], v[50:65]
	ds_read_b64_tr_b16 v[182:183], v235 offset:8192
	ds_read_b64_tr_b16 v[184:185], v235 offset:10240
	s_waitcnt lgkmcnt(10)
	v_mfma_f32_32x32x16_bf16 v[34:49], v[222:225], v[174:177], v[34:49]
	ds_read_b64_tr_b16 v[222:223], v227 offset:8192
	ds_read_b64_tr_b16 v[224:225], v227 offset:10240
	s_waitcnt lgkmcnt(10)
	v_mfma_f32_32x32x16_bf16 v[18:33], v[228:231], v[174:177], v[18:33]
	ds_read_b64_tr_b16 v[228:229], v226 offset:12288
	ds_read_b64_tr_b16 v[230:231], v226 offset:14336
	s_waitcnt lgkmcnt(10)
	v_mfma_f32_32x32x16_bf16 v[2:17], v[240:243], v[174:177], v[2:17]
	ds_read_b64_tr_b16 v[240:241], v207 offset:12288
	ds_read_b64_tr_b16 v[242:243], v207 offset:14336
	s_waitcnt lgkmcnt(10)
	v_mfma_f32_32x32x16_bf16 v[50:65], v[244:247], v[166:169], v[50:65]
	ds_read_b64_tr_b16 v[244:245], v235 offset:12288
	ds_read_b64_tr_b16 v[246:247], v235 offset:14336
	s_waitcnt lgkmcnt(10)
	v_mfma_f32_32x32x16_bf16 v[34:49], v[248:251], v[166:169], v[34:49]
	ds_read_b64_tr_b16 v[248:249], v227 offset:12288
	ds_read_b64_tr_b16 v[250:251], v227 offset:14336
	s_waitcnt lgkmcnt(10)
	v_mfma_f32_32x32x16_bf16 v[18:33], v[182:185], v[166:169], v[18:33]
	s_waitcnt lgkmcnt(8)
	v_mfma_f32_32x32x16_bf16 v[2:17], v[222:225], v[166:169], v[2:17]
	s_waitcnt lgkmcnt(6)
	v_mfma_f32_32x32x16_bf16 v[50:65], v[228:231], v[162:165], v[50:65]
	s_waitcnt lgkmcnt(4)
	v_mfma_f32_32x32x16_bf16 v[34:49], v[240:243], v[162:165], v[34:49]
	s_waitcnt lgkmcnt(2)
	v_mfma_f32_32x32x16_bf16 v[18:33], v[244:247], v[162:165], v[18:33]
	s_waitcnt lgkmcnt(0)
	v_mfma_f32_32x32x16_bf16 v[2:17], v[248:251], v[162:165], v[2:17]
	s_setprio 0
	s_and_b64 vcc, exec, s[40:41]
	s_cbranch_vccnz .LBB0_581
; DI void attn_unit(const bf16_t* Q, const bf16_t* Kp, const bf16_t* Vp, bf16_t* O, size_t qrow0, size_t krow0, int ntile, int h, float lam, float lam_init, const float* gsub, LAS unsigned char* lds) {
;     ...
;         if (!shifted) {
;             ps = 0.f;
; #pragma unroll
;             for (int kh = 0; kh < 2; ++kh)
; #pragma unroll
;                 for (int i = 0; i < 16; ++i) { sn[kh][i] = __builtin_amdgcn_exp2f(sn[kh][i]); ps += sn[kh][i]; }
;             l_run += ps;
;         }
	v_exp_f32_e32 v114, v114
	v_exp_f32_e32 v115, v115
	v_exp_f32_e32 v116, v116
	v_exp_f32_e32 v117, v117
	v_add_f32_e32 v1, 0, v114
	v_exp_f32_e32 v118, v118
	v_add_f32_e32 v1, v115, v1
	v_exp_f32_e32 v119, v119
	v_add_f32_e32 v1, v116, v1
	v_exp_f32_e32 v120, v120
	v_add_f32_e32 v1, v117, v1
	v_exp_f32_e32 v121, v121
	v_add_f32_e32 v1, v118, v1
	v_exp_f32_e32 v122, v122
	v_add_f32_e32 v1, v119, v1
	v_exp_f32_e32 v123, v123
	v_add_f32_e32 v1, v120, v1
	v_exp_f32_e32 v124, v124
	v_add_f32_e32 v1, v121, v1
	v_exp_f32_e32 v125, v125
	v_add_f32_e32 v1, v122, v1
	v_exp_f32_e32 v126, v126
	v_add_f32_e32 v1, v123, v1
	v_exp_f32_e32 v127, v127
	v_add_f32_e32 v1, v124, v1
	v_exp_f32_e32 v128, v128
	v_add_f32_e32 v1, v125, v1
	v_exp_f32_e32 v129, v129
	v_add_f32_e32 v1, v126, v1
	v_exp_f32_e32 v130, v130
	v_add_f32_e32 v1, v127, v1
	v_exp_f32_e32 v131, v131
	v_add_f32_e32 v1, v128, v1
	v_exp_f32_e32 v132, v132
	v_add_f32_e32 v1, v129, v1
	v_exp_f32_e32 v133, v133
	v_add_f32_e32 v1, v130, v1
	v_exp_f32_e32 v134, v134
	v_add_f32_e32 v1, v131, v1
	v_exp_f32_e32 v135, v135
	v_add_f32_e32 v1, v132, v1
	v_exp_f32_e32 v136, v136
	v_add_f32_e32 v1, v133, v1
	v_exp_f32_e32 v137, v137
	v_add_f32_e32 v1, v134, v1
	v_exp_f32_e32 v138, v138
	v_add_f32_e32 v1, v135, v1
	v_exp_f32_e32 v139, v139
	v_add_f32_e32 v1, v136, v1
	v_exp_f32_e32 v140, v140
	v_add_f32_e32 v1, v137, v1
	v_exp_f32_e32 v141, v141
	v_add_f32_e32 v1, v138, v1
	v_exp_f32_e32 v142, v142
	v_add_f32_e32 v1, v139, v1
	v_exp_f32_e32 v143, v143
	v_add_f32_e32 v1, v140, v1
	v_exp_f32_e32 v144, v144
	v_add_f32_e32 v1, v141, v1
	v_exp_f32_e32 v145, v145
	v_add_f32_e32 v1, v142, v1
	v_add_f32_e32 v1, v143, v1
	v_add_f32_e32 v1, v144, v1
	v_add_f32_e32 v220, v145, v1
	v_add_f32_e32 v213, v213, v220
